# P0 row conversion: all 16 row loads issued up front (was load-wait-store serialized); P8 final norm: g_final chunk loads hoisted out of the serialized store loop
# speedup vs baseline: 1.0217x; 1.0025x over previous
; #define GAS __attribute__((address_space(1)))
; __device__ __forceinline__ unsigned pk2(float lo, float hi) { return pg8::cvt_pk_bf16(lo, hi); }
; __device__ __forceinline__ void p0_row(const float* xrow, bf16* orow, float* rs, int lane) {
;     float s = 0.f; GAS v2u* o8 = (GAS v2u*)orow + lane;
;     if (xrow) { const GAS f32x4* xr = (const GAS f32x4*)xrow + lane;
; #pragma unroll
;         for (int j = 0; j < 16; ++j) { const f32x4 v = xr[64 * j]; s += (v.x * v.x + v.y * v.y) + (v.z * v.z + v.w * v.w); v2u w; w.x = pk2(v.x, v.y); w.y = pk2(v.z, v.w); o8[64 * j] = w; }
;     } else {
; #pragma unroll
;         for (int j = 0; j < 16; ++j) { v2u w; w.x = 0u; w.y = 0u; o8[64 * j] = w; } }
;     s = wave_sum(s);
;     if (lane == 0) *rs = 1.f / sqrtf(s * (1.f / 4096.f) + EPS);
; }
.LBB0_293:
	v_lshl_add_u64 v[26:27], s[10:11], 0, v[24:25]
	s_cmp_lg_u64 s[8:9], 0
	v_lshl_add_u64 v[28:29], v[26:27], 0, s[28:29]
	s_cbranch_scc0 .LBB0_298
	s_add_u32 s98, s8, 0x1000
	s_addc_u32 s99, s9, 0
	s_add_u32 s100, s8, 0x2000
	s_addc_u32 s101, s9, 0
	s_add_u32 vcc_lo, s8, 0x3000
	s_addc_u32 vcc_hi, s9, 0
	global_load_dwordx4 v[80:83], v22, s[8:9]
	global_load_dwordx4 v[84:87], v22, s[8:9] offset:1024
	global_load_dwordx4 v[88:91], v22, s[8:9] offset:2048
	global_load_dwordx4 v[92:95], v22, s[8:9] offset:3072
	global_load_dwordx4 v[96:99], v22, s[98:99]
	global_load_dwordx4 v[100:103], v22, s[98:99] offset:1024
	global_load_dwordx4 v[104:107], v22, s[98:99] offset:2048
	global_load_dwordx4 v[108:111], v22, s[98:99] offset:3072
	global_load_dwordx4 v[112:115], v22, s[100:101]
	global_load_dwordx4 v[116:119], v22, s[100:101] offset:1024
	global_load_dwordx4 v[120:123], v22, s[100:101] offset:2048
	global_load_dwordx4 v[124:127], v22, s[100:101] offset:3072
	global_load_dwordx4 v[128:131], v22, vcc
	global_load_dwordx4 v[132:135], v22, vcc offset:1024
	global_load_dwordx4 v[136:139], v22, vcc offset:2048
	global_load_dwordx4 v[140:143], v22, vcc offset:3072
	s_waitcnt vmcnt(15)
	v_mov_b64_e32 v[2:3], v[80:81]
	v_mov_b64_e32 v[4:5], v[82:83]
	v_cvt_pk_bf16_f32 v6, v2, v3
	v_cvt_pk_bf16_f32 v7, v4, v5
	global_store_dwordx2 v[28:29], v[6:7], off
	s_waitcnt vmcnt(15)
	v_mov_b64_e32 v[6:7], v[84:85]
	v_mov_b64_e32 v[8:9], v[86:87]
	v_add_co_u32_e32 v44, vcc, s3, v26
	v_cvt_pk_bf16_f32 v10, v6, v7
	v_cvt_pk_bf16_f32 v11, v8, v9
	v_lshl_add_u64 v[60:61], s[8:9], 0, v[22:23]
	v_addc_co_u32_e32 v45, vcc, 0, v27, vcc
	global_store_dwordx2 v[44:45], v[10:11], off offset:512
	s_waitcnt vmcnt(15)
	v_mov_b64_e32 v[10:11], v[88:89]
	v_mov_b64_e32 v[12:13], v[90:91]
	v_cvt_pk_bf16_f32 v14, v10, v11
	v_cvt_pk_bf16_f32 v15, v12, v13
	global_store_dwordx2 v[44:45], v[14:15], off offset:1024
	s_waitcnt vmcnt(15)
	v_mov_b64_e32 v[14:15], v[92:93]
	v_mov_b64_e32 v[16:17], v[94:95]
	v_add_co_u32_e32 v56, vcc, s5, v60
	v_cvt_pk_bf16_f32 v18, v14, v15
	v_cvt_pk_bf16_f32 v19, v16, v17
	global_store_dwordx2 v[44:45], v[18:19], off offset:1536
	v_addc_co_u32_e32 v57, vcc, 0, v61, vcc
	s_waitcnt vmcnt(15)
	v_mov_b64_e32 v[18:19], v[96:97]
	v_mov_b64_e32 v[20:21], v[98:99]
	v_add_co_u32_e32 v40, vcc, s4, v60
	v_cvt_pk_bf16_f32 v32, v18, v19
	v_cvt_pk_bf16_f32 v33, v20, v21
	global_store_dwordx2 v[44:45], v[32:33], off offset:2048
	v_addc_co_u32_e32 v41, vcc, 0, v61, vcc
	s_waitcnt vmcnt(15)
	v_mov_b64_e32 v[32:33], v[100:101]
	v_mov_b64_e32 v[34:35], v[102:103]
	v_cvt_pk_bf16_f32 v36, v32, v33
	v_cvt_pk_bf16_f32 v37, v34, v35
	global_store_dwordx2 v[44:45], v[36:37], off offset:2560
	s_waitcnt vmcnt(15)
	v_mov_b64_e32 v[36:37], v[104:105]
	v_mov_b64_e32 v[38:39], v[106:107]
	v_cvt_pk_bf16_f32 v42, v36, v37
	v_cvt_pk_bf16_f32 v43, v38, v39
	global_store_dwordx2 v[44:45], v[42:43], off offset:3072
	s_waitcnt vmcnt(15)
	v_mov_b64_e32 v[40:41], v[108:109]
	v_mov_b64_e32 v[42:43], v[110:111]
	v_cvt_pk_bf16_f32 v46, v40, v41
	v_cvt_pk_bf16_f32 v47, v42, v43
	global_store_dwordx2 v[44:45], v[46:47], off offset:3584
	v_add_co_u32_e32 v72, vcc, s21, v26
	s_waitcnt vmcnt(15)
	v_mov_b64_e32 v[44:45], v[112:113]
	v_mov_b64_e32 v[46:47], v[114:115]
	s_nop 0
	v_addc_co_u32_e32 v73, vcc, 0, v27, vcc
	v_cvt_pk_bf16_f32 v48, v44, v45
	v_cvt_pk_bf16_f32 v49, v46, v47
	global_store_dwordx2 v[72:73], v[48:49], off
	s_waitcnt vmcnt(15)
	v_mov_b64_e32 v[48:49], v[116:117]
	v_mov_b64_e32 v[50:51], v[118:119]
	v_cvt_pk_bf16_f32 v52, v48, v49
	v_cvt_pk_bf16_f32 v53, v50, v51
	global_store_dwordx2 v[72:73], v[52:53], off offset:512
	s_waitcnt vmcnt(15)
	v_mov_b64_e32 v[52:53], v[120:121]
	v_mov_b64_e32 v[54:55], v[122:123]
	v_cvt_pk_bf16_f32 v58, v52, v53
	v_cvt_pk_bf16_f32 v59, v54, v55
	global_store_dwordx2 v[72:73], v[58:59], off offset:1024
	s_waitcnt vmcnt(15)
	v_mov_b64_e32 v[56:57], v[124:125]
	v_mov_b64_e32 v[58:59], v[126:127]
	v_add_co_u32_e32 v74, vcc, s34, v60
	v_cvt_pk_bf16_f32 v60, v56, v57
	s_nop 0
	v_addc_co_u32_e32 v75, vcc, 0, v61, vcc
	v_cvt_pk_bf16_f32 v61, v58, v59
	global_store_dwordx2 v[72:73], v[60:61], off offset:1536
	s_waitcnt vmcnt(15)
	v_mov_b64_e32 v[60:61], v[128:129]
	v_mov_b64_e32 v[62:63], v[130:131]
	v_cvt_pk_bf16_f32 v64, v60, v61
	v_cvt_pk_bf16_f32 v65, v62, v63
	global_store_dwordx2 v[72:73], v[64:65], off offset:2048
	s_waitcnt vmcnt(15)
; __device__ __forceinline__ unsigned pk2(float lo, float hi) { return pg8::cvt_pk_bf16(lo, hi); }
; __device__ __forceinline__ void p0_row(const float* xrow, bf16* orow, float* rs, int lane) {
;     ...
;         for (int j = 0; j < 16; ++j) { const f32x4 v = xr[64 * j]; s += (v.x * v.x + v.y * v.y) + (v.z * v.z + v.w * v.w); v2u w; w.x = pk2(v.x, v.y); w.y = pk2(v.z, v.w); o8[64 * j] = w; }
;     } else {
; #pragma unroll
;         for (int j = 0; j < 16; ++j) { v2u w; w.x = 0u; w.y = 0u; o8[64 * j] = w; } }
;     s = wave_sum(s);
;     if (lane == 0) *rs = 1.f / sqrtf(s * (1.f / 4096.f) + EPS);
	v_mov_b64_e32 v[64:65], v[132:133]
	v_mov_b64_e32 v[66:67], v[134:135]
	v_cvt_pk_bf16_f32 v68, v64, v65
	v_cvt_pk_bf16_f32 v69, v66, v67
	global_store_dwordx2 v[72:73], v[68:69], off offset:2560
	s_waitcnt vmcnt(15)
	v_mov_b64_e32 v[68:69], v[136:137]
	v_mov_b64_e32 v[70:71], v[138:139]
	v_pk_mul_f32 v[4:5], v[4:5], v[4:5]
	v_pk_mul_f32 v[2:3], v[2:3], v[2:3]
	v_pk_mul_f32 v[6:7], v[6:7], v[6:7]
	v_pk_mov_b32 v[76:77], v[2:3], v[4:5] op_sel:[1,0]
	v_mov_b32_e32 v3, v5
	v_pk_mul_f32 v[4:5], v[8:9], v[8:9]
	v_pk_add_f32 v[2:3], v[76:77], v[2:3]
	v_pk_mov_b32 v[8:9], v[6:7], v[4:5] op_sel:[1,0]
	v_mov_b32_e32 v7, v5
	v_pk_add_f32 v[4:5], v[8:9], v[6:7]
	v_pk_add_f32 v[2:3], v[2:3], v[2:3] op_sel:[0,1] op_sel_hi:[1,0]
	v_pk_add_f32 v[4:5], v[4:5], v[4:5] op_sel:[0,1] op_sel_hi:[1,0]
	v_mul_f32_e32 v6, v11, v11
	v_pk_fma_f32 v[6:7], v[10:11], v[10:11], v[6:7] op_sel_hi:[1,1,0]
	v_mul_f32_e32 v8, v13, v13
	v_mul_f32_e32 v3, v14, v14
	v_mul_f32_e32 v5, v15, v15
	v_pk_add_f32 v[10:11], v[2:3], v[4:5]
	v_cvt_pk_bf16_f32 v2, v68, v69
	v_cvt_pk_bf16_f32 v3, v70, v71
	global_store_dwordx2 v[72:73], v[2:3], off offset:3072
	s_waitcnt vmcnt(15)
	v_mov_b64_e32 v[2:3], v[140:141]
	v_mov_b64_e32 v[4:5], v[142:143]
	v_pk_fma_f32 v[8:9], v[12:13], v[12:13], v[8:9] op_sel_hi:[1,1,0]
	v_mul_f32_e32 v7, v16, v16
	v_mul_f32_e32 v9, v17, v17
	v_pk_add_f32 v[6:7], v[6:7], v[8:9]
	v_pk_mul_f32 v[8:9], v[20:21], v[20:21]
	v_pk_add_f32 v[6:7], v[10:11], v[6:7]
	v_pk_mul_f32 v[10:11], v[18:19], v[18:19]
	v_pk_add_f32 v[6:7], v[6:7], v[6:7] op_sel:[0,1] op_sel_hi:[1,0]
	v_pk_mov_b32 v[12:13], v[10:11], v[8:9] op_sel:[1,0]
	v_mov_b32_e32 v11, v9
	v_pk_add_f32 v[8:9], v[12:13], v[10:11]
	v_mul_f32_e32 v10, v33, v33
	v_mul_f32_e32 v12, v35, v35
	v_pk_add_f32 v[8:9], v[8:9], v[8:9] op_sel:[0,1] op_sel_hi:[1,0]
	v_pk_fma_f32 v[10:11], v[32:33], v[32:33], v[10:11] op_sel_hi:[1,1,0]
	v_pk_fma_f32 v[12:13], v[34:35], v[34:35], v[12:13] op_sel_hi:[1,1,0]
	v_mul_f32_e32 v7, v36, v36
	v_mul_f32_e32 v9, v37, v37
	v_mul_f32_e32 v11, v38, v38
	v_mul_f32_e32 v13, v39, v39
	v_pk_add_f32 v[6:7], v[6:7], v[8:9]
	v_pk_add_f32 v[8:9], v[10:11], v[12:13]
	v_pk_mul_f32 v[10:11], v[40:41], v[40:41]
	v_pk_add_f32 v[6:7], v[6:7], v[8:9]
	v_pk_mul_f32 v[8:9], v[42:43], v[42:43]
	v_pk_add_f32 v[6:7], v[6:7], v[6:7] op_sel:[0,1] op_sel_hi:[1,0]
	v_pk_mov_b32 v[12:13], v[10:11], v[8:9] op_sel:[1,0]
	v_mov_b32_e32 v11, v9
	v_pk_add_f32 v[8:9], v[12:13], v[10:11]
	v_mul_f32_e32 v10, v45, v45
	v_mul_f32_e32 v12, v47, v47
	v_pk_add_f32 v[8:9], v[8:9], v[8:9] op_sel:[0,1] op_sel_hi:[1,0]
	v_pk_fma_f32 v[10:11], v[44:45], v[44:45], v[10:11] op_sel_hi:[1,1,0]
	v_pk_fma_f32 v[12:13], v[46:47], v[46:47], v[12:13] op_sel_hi:[1,1,0]
	v_mul_f32_e32 v7, v48, v48
	v_mul_f32_e32 v9, v49, v49
	v_mul_f32_e32 v11, v50, v50
	v_mul_f32_e32 v13, v51, v51
	v_pk_add_f32 v[6:7], v[6:7], v[8:9]
	v_pk_add_f32 v[8:9], v[10:11], v[12:13]
	v_pk_mul_f32 v[10:11], v[52:53], v[52:53]
	v_pk_add_f32 v[6:7], v[6:7], v[8:9]
	v_pk_mul_f32 v[8:9], v[54:55], v[54:55]
	v_pk_add_f32 v[6:7], v[6:7], v[6:7] op_sel:[0,1] op_sel_hi:[1,0]
	v_pk_mov_b32 v[12:13], v[10:11], v[8:9] op_sel:[1,0]
	v_mov_b32_e32 v11, v9
	v_pk_add_f32 v[8:9], v[12:13], v[10:11]
	v_mul_f32_e32 v10, v57, v57
	v_mul_f32_e32 v12, v59, v59
	v_pk_add_f32 v[8:9], v[8:9], v[8:9] op_sel:[0,1] op_sel_hi:[1,0]
	v_pk_fma_f32 v[10:11], v[56:57], v[56:57], v[10:11] op_sel_hi:[1,1,0]
	v_pk_fma_f32 v[12:13], v[58:59], v[58:59], v[12:13] op_sel_hi:[1,1,0]
	v_mul_f32_e32 v7, v60, v60
	v_mul_f32_e32 v9, v61, v61
	v_mul_f32_e32 v11, v62, v62
	v_mul_f32_e32 v13, v63, v63
	v_pk_add_f32 v[6:7], v[6:7], v[8:9]
	v_pk_add_f32 v[8:9], v[10:11], v[12:13]
	v_pk_mul_f32 v[10:11], v[64:65], v[64:65]
	v_pk_add_f32 v[6:7], v[6:7], v[8:9]
	v_pk_mul_f32 v[8:9], v[66:67], v[66:67]
	v_pk_add_f32 v[6:7], v[6:7], v[6:7] op_sel:[0,1] op_sel_hi:[1,0]
	v_pk_mov_b32 v[12:13], v[10:11], v[8:9] op_sel:[1,0]
	v_mov_b32_e32 v11, v9
	v_pk_add_f32 v[8:9], v[12:13], v[10:11]
	v_mul_f32_e32 v10, v69, v69
	v_mul_f32_e32 v12, v71, v71
	v_pk_add_f32 v[8:9], v[8:9], v[8:9] op_sel:[0,1] op_sel_hi:[1,0]
	v_pk_fma_f32 v[10:11], v[68:69], v[68:69], v[10:11] op_sel_hi:[1,1,0]
	v_pk_fma_f32 v[12:13], v[70:71], v[70:71], v[12:13] op_sel_hi:[1,1,0]
	v_mul_f32_e32 v7, v2, v2
	v_mul_f32_e32 v9, v3, v3
	v_mul_f32_e32 v11, v4, v4
	v_mul_f32_e32 v13, v5, v5
	v_cvt_pk_bf16_f32 v2, v2, v3
	v_cvt_pk_bf16_f32 v3, v4, v5
	v_pk_add_f32 v[4:5], v[6:7], v[8:9]
	v_pk_add_f32 v[6:7], v[10:11], v[12:13]
	s_nop 0
	v_pk_add_f32 v[4:5], v[4:5], v[6:7]
	s_nop 0
	v_add_f32_e32 v4, v4, v5
	s_cbranch_execnz .LBB0_296

; #define GAS __attribute__((address_space(1)))
; __global__ void __launch_bounds__(NTHR, 2) fwd_kernel(Args args) {
;     ...
;         f32x4 v[16]; float s = 0.f;
;         if (m >= 256 && m < 16640) {
; #pragma unroll
;             for (int j = 0; j < 16; ++j) v[j] = yr[64 * j];
;         } else { const int slot = m < 256 ? m : 256 + (m - 16640);
; #pragma unroll
;             for (int j = 0; j < 16; ++j) { const v2u hw = *((const GAS v2u*)(H1B + (size_t)m * 4096) + lane + 64 * j); f32x4 a; a.x = __builtin_bit_cast(float, hw.x << 16); a.y = __builtin_bit_cast(float, hw.x & 0xffff0000u); a.z = __builtin_bit_cast(float, hw.y << 16); a.w = __builtin_bit_cast(float, hw.y & 0xffff0000u);
; #pragma unroll
;                 for (int ks = 0; ks < 8; ++ks) a = a + *((const GAS f32x4*)(SLAB + ((size_t)ks * 512 + slot) * 4096) + lane + 64 * j);
;                 v[j] = a; } }
; #pragma unroll
;         for (int j = 0; j < 16; ++j) s += (v[j].x * v[j].x + v[j].y * v[j].y) + (v[j].z * v[j].z + v[j].w * v[j].w);
;         s = wave_sum(s);
;         const float sc = 1.f / sqrtf(s * (1.f / 4096.f) + EPS);
; #pragma unroll
;         for (int j = 0; j < 16; ++j) { const f32x4 gg = gf[64 * j]; yr[64 * j] = v[j] * sc * gg; }
.LBB0_3607:
	s_waitcnt vmcnt(15)
	v_mul_f32_e32 v66, v1, v1
	v_mul_f32_e32 v67, v3, v3
	v_fmac_f32_e32 v66, v0, v0
	v_fmac_f32_e32 v67, v2, v2
	v_add_f32_e32 v66, v66, v67
	s_waitcnt vmcnt(14)
	v_mul_f32_e32 v67, v5, v5
	v_mul_f32_e32 v68, v7, v7
	v_fmac_f32_e32 v67, v4, v4
	v_fmac_f32_e32 v68, v6, v6
	v_add_f32_e32 v67, v67, v68
	v_add_f32_e32 v66, v66, v67
	s_waitcnt vmcnt(13)
	v_mul_f32_e32 v67, v9, v9
	v_mul_f32_e32 v68, v11, v11
	v_fmac_f32_e32 v67, v8, v8
	v_fmac_f32_e32 v68, v10, v10
	v_add_f32_e32 v67, v67, v68
	v_add_f32_e32 v66, v66, v67
	s_waitcnt vmcnt(12)
	v_mul_f32_e32 v67, v13, v13
	v_mul_f32_e32 v68, v15, v15
	v_fmac_f32_e32 v67, v12, v12
	v_fmac_f32_e32 v68, v14, v14
	v_add_f32_e32 v67, v67, v68
	v_add_f32_e32 v66, v66, v67
	s_waitcnt vmcnt(11)
	v_mul_f32_e32 v67, v17, v17
	v_mul_f32_e32 v68, v19, v19
	v_fmac_f32_e32 v67, v16, v16
	v_fmac_f32_e32 v68, v18, v18
	v_add_f32_e32 v67, v67, v68
	v_add_f32_e32 v66, v66, v67
	s_waitcnt vmcnt(10)
	v_mul_f32_e32 v67, v21, v21
	v_mul_f32_e32 v68, v23, v23
	v_fmac_f32_e32 v67, v20, v20
	v_fmac_f32_e32 v68, v22, v22
	v_add_f32_e32 v67, v67, v68
	v_add_f32_e32 v66, v66, v67
	s_waitcnt vmcnt(9)
	v_mul_f32_e32 v67, v25, v25
	v_mul_f32_e32 v68, v27, v27
	v_fmac_f32_e32 v67, v24, v24
	v_fmac_f32_e32 v68, v26, v26
	v_add_f32_e32 v67, v67, v68
	v_add_f32_e32 v66, v66, v67
	s_waitcnt vmcnt(8)
	v_mul_f32_e32 v67, v29, v29
	v_mul_f32_e32 v68, v31, v31
	v_fmac_f32_e32 v67, v28, v28
	v_fmac_f32_e32 v68, v30, v30
	v_add_f32_e32 v67, v67, v68
	v_add_f32_e32 v66, v66, v67
	s_waitcnt vmcnt(7)
	v_mul_f32_e32 v67, v33, v33
	v_mul_f32_e32 v68, v35, v35
	v_fmac_f32_e32 v67, v32, v32
	v_fmac_f32_e32 v68, v34, v34
	v_add_f32_e32 v67, v67, v68
	v_add_f32_e32 v66, v66, v67
	s_waitcnt vmcnt(6)
	v_mul_f32_e32 v67, v37, v37
	v_mul_f32_e32 v68, v39, v39
	v_fmac_f32_e32 v67, v36, v36
	v_fmac_f32_e32 v68, v38, v38
	v_add_f32_e32 v67, v67, v68
	v_add_f32_e32 v66, v66, v67
	s_waitcnt vmcnt(5)
	v_mul_f32_e32 v67, v41, v41
	v_mul_f32_e32 v68, v43, v43
	v_fmac_f32_e32 v67, v40, v40
	v_fmac_f32_e32 v68, v42, v42
	v_add_f32_e32 v67, v67, v68
	v_add_f32_e32 v70, v66, v67
	global_load_dwordx4 v[66:69], v[90:91], off
	s_waitcnt vmcnt(5)
	v_mul_f32_e32 v71, v45, v45
	v_mul_f32_e32 v72, v47, v47
	v_fmac_f32_e32 v71, v44, v44
	v_fmac_f32_e32 v72, v46, v46
	v_add_f32_e32 v71, v71, v72
	v_add_f32_e32 v70, v70, v71
	s_waitcnt vmcnt(4)
	v_mul_f32_e32 v71, v49, v49
	v_mul_f32_e32 v72, v51, v51
	v_fmac_f32_e32 v71, v48, v48
	v_fmac_f32_e32 v72, v50, v50
	v_add_f32_e32 v71, v71, v72
	v_add_f32_e32 v70, v70, v71
	s_waitcnt vmcnt(3)
	v_mul_f32_e32 v71, v53, v53
	v_mul_f32_e32 v72, v55, v55
	v_fmac_f32_e32 v71, v52, v52
	v_fmac_f32_e32 v72, v54, v54
	v_add_f32_e32 v71, v71, v72
	v_add_f32_e32 v70, v70, v71
	s_waitcnt vmcnt(2)
	v_mul_f32_e32 v71, v57, v57
	v_mul_f32_e32 v72, v59, v59
	v_fmac_f32_e32 v71, v56, v56
	v_fmac_f32_e32 v72, v58, v58
	v_add_f32_e32 v71, v71, v72
	v_add_f32_e32 v70, v70, v71
	s_waitcnt vmcnt(1)
	v_mul_f32_e32 v71, v61, v61
	v_mul_f32_e32 v72, v63, v63
	v_fmac_f32_e32 v71, v60, v60
	v_fmac_f32_e32 v72, v62, v62
	v_add_f32_e32 v71, v71, v72
	v_add_f32_e32 v70, v70, v71
	global_load_dwordx4 v[160:163], v[90:91], off offset:1024
	global_load_dwordx4 v[164:167], v[90:91], off offset:2048
	global_load_dwordx4 v[168:171], v[90:91], off offset:3072
	global_load_dwordx4 v[172:175], v[120:121], off
	global_load_dwordx4 v[176:179], v[122:123], off
	global_load_dwordx4 v[180:183], v[124:125], off
	global_load_dwordx4 v[184:187], v[126:127], off
	global_load_dwordx4 v[188:191], v[128:129], off
	global_load_dwordx4 v[192:195], v[130:131], off
	global_load_dwordx4 v[196:199], v[132:133], off
	global_load_dwordx4 v[200:203], v[134:135], off
	global_load_dwordx4 v[204:207], v[136:137], off
	global_load_dwordx4 v[208:211], v[138:139], off
	global_load_dwordx4 v[212:215], v[140:141], off
	global_load_dwordx4 v[216:219], v[142:143], off
	v_mov_b32_e32 v71, v89
	s_nop 0
	v_add_f32_dpp v70, v70, v70 quad_perm:[1,0,3,2] row_mask:0xf bank_mask:0xf bound_ctrl:1
	s_nop 1
	v_add_f32_dpp v70, v70, v70 quad_perm:[2,3,0,1] row_mask:0xf bank_mask:0xf bound_ctrl:1
	s_nop 1
	v_add_f32_dpp v70, v70, v70 row_half_mirror row_mask:0xf bank_mask:0xf bound_ctrl:1
	s_nop 1
	v_add_f32_dpp v70, v70, v70 row_mirror row_mask:0xf bank_mask:0xf bound_ctrl:1
	s_nop 1
	v_mov_b32_dpp v71, v70 row_bcast:15 row_mask:0xa bank_mask:0xf
	v_add_f32_e32 v70, v70, v71
	v_mov_b32_e32 v71, v89
	s_nop 1
	v_mov_b32_dpp v71, v70 row_bcast:31 row_mask:0xc bank_mask:0xf
	v_add_f32_e32 v70, v70, v71
	s_nop 0
	v_readlane_b32 s0, v70, 63
	s_nop 1
	v_fma_f32 v70, s0, v154, v152
	v_mul_f32_e32 v71, 0x4f800000, v70
	v_cmp_gt_f32_e32 vcc, s26, v70
	s_nop 1
	v_cndmask_b32_e32 v70, v70, v71, vcc
	v_sqrt_f32_e32 v71, v70
	s_nop 0
	v_add_u32_e32 v72, -1, v71
	v_fma_f32 v73, -v72, v71, v70
	v_cmp_ge_f32_e64 s[0:1], 0, v73
	v_add_u32_e32 v73, 1, v71
	s_nop 0
	v_cndmask_b32_e64 v72, v71, v72, s[0:1]
	v_fma_f32 v71, -v73, v71, v70
	v_cmp_lt_f32_e64 s[0:1], 0, v71
	s_nop 1
	v_cndmask_b32_e64 v71, v72, v73, s[0:1]
	v_mul_f32_e32 v72, 0x37800000, v71
	v_cndmask_b32_e32 v71, v71, v72, vcc
	v_cmp_class_f32_e32 vcc, v70, v153
	s_nop 1
	v_cndmask_b32_e32 v70, v71, v70, vcc
	v_div_scale_f32 v71, s[0:1], v70, v70, 1.0
	v_rcp_f32_e32 v72, v71
	s_nop 0
	v_fma_f32 v73, -v71, v72, 1.0
	v_fmac_f32_e32 v72, v73, v72
	v_div_scale_f32 v73, vcc, 1.0, v70, 1.0
	v_mul_f32_e32 v74, v73, v72
	v_fma_f32 v75, -v71, v74, v73
	v_fmac_f32_e32 v74, v75, v72
	v_fma_f32 v71, -v71, v74, v73
	v_div_fmas_f32 v71, v71, v72, v74
	v_div_fixup_f32 v70, v71, v70, 1.0
	v_pk_mul_f32 v[0:1], v[70:71], v[0:1] op_sel_hi:[0,1]
	v_pk_mul_f32 v[2:3], v[70:71], v[2:3] op_sel_hi:[0,1]
	s_waitcnt vmcnt(0)
; __global__ void __launch_bounds__(NTHR, 2) fwd_kernel(Args args) {
;     ...
; #pragma unroll
;         for (int j = 0; j < 16; ++j) { const f32x4 gg = gf[64 * j]; yr[64 * j] = v[j] * sc * gg; }
	v_pk_mul_f32 v[2:3], v[68:69], v[2:3]
	v_pk_mul_f32 v[0:1], v[66:67], v[0:1]
	global_store_dwordx4 v[64:65], v[0:3], off
	v_pk_mul_f32 v[6:7], v[70:71], v[6:7] op_sel_hi:[0,1]
	v_pk_mul_f32 v[4:5], v[70:71], v[4:5] op_sel_hi:[0,1]
	v_pk_mul_f32 v[0:1], v[160:161], v[4:5]
	v_pk_mul_f32 v[2:3], v[162:163], v[6:7]
	global_store_dwordx4 v[64:65], v[0:3], off offset:1024
	v_pk_mul_f32 v[4:5], v[70:71], v[10:11] op_sel_hi:[0,1]
	v_pk_mul_f32 v[6:7], v[70:71], v[8:9] op_sel_hi:[0,1]
	v_pk_mul_f32 v[8:9], v[70:71], v[16:17] op_sel_hi:[0,1]
	v_pk_mul_f32 v[10:11], v[70:71], v[20:21] op_sel_hi:[0,1]
	v_pk_mul_f32 v[0:1], v[164:165], v[6:7]
	v_pk_mul_f32 v[2:3], v[166:167], v[4:5]
	global_store_dwordx4 v[64:65], v[0:3], off offset:2048
	v_pk_mul_f32 v[4:5], v[70:71], v[14:15] op_sel_hi:[0,1]
	v_pk_mul_f32 v[6:7], v[70:71], v[12:13] op_sel_hi:[0,1]
	v_pk_mul_f32 v[0:1], v[168:169], v[6:7]
	v_pk_mul_f32 v[2:3], v[170:171], v[4:5]
	global_store_dwordx4 v[64:65], v[0:3], off offset:3072
	v_add_co_u32_e32 v4, vcc, s24, v64
	v_pk_mul_f32 v[6:7], v[70:71], v[18:19] op_sel_hi:[0,1]
	s_nop 0
	v_addc_co_u32_e32 v5, vcc, 0, v65, vcc
	v_pk_mul_f32 v[0:1], v[172:173], v[8:9]
	v_pk_mul_f32 v[2:3], v[174:175], v[6:7]
	global_store_dwordx4 v[4:5], v[0:3], off offset:-4096
	v_add_co_u32_e32 v6, vcc, s23, v64
	v_pk_mul_f32 v[8:9], v[70:71], v[22:23] op_sel_hi:[0,1]
	s_nop 0
	v_addc_co_u32_e32 v7, vcc, 0, v65, vcc
	v_pk_mul_f32 v[0:1], v[176:177], v[10:11]
	v_pk_mul_f32 v[2:3], v[178:179], v[8:9]
	global_store_dwordx4 v[6:7], v[0:3], off offset:1024
	v_pk_mul_f32 v[8:9], v[70:71], v[26:27] op_sel_hi:[0,1]
	v_pk_mul_f32 v[10:11], v[70:71], v[24:25] op_sel_hi:[0,1]
	v_pk_mul_f32 v[0:1], v[180:181], v[10:11]
	v_pk_mul_f32 v[2:3], v[182:183], v[8:9]
	global_store_dwordx4 v[6:7], v[0:3], off offset:2048
	v_pk_mul_f32 v[8:9], v[70:71], v[30:31] op_sel_hi:[0,1]
	v_pk_mul_f32 v[10:11], v[70:71], v[28:29] op_sel_hi:[0,1]
	v_pk_mul_f32 v[0:1], v[184:185], v[10:11]
	v_pk_mul_f32 v[2:3], v[186:187], v[8:9]
	global_store_dwordx4 v[6:7], v[0:3], off offset:3072
	v_pk_mul_f32 v[6:7], v[70:71], v[34:35] op_sel_hi:[0,1]
	v_pk_mul_f32 v[8:9], v[70:71], v[32:33] op_sel_hi:[0,1]
	v_pk_mul_f32 v[0:1], v[188:189], v[8:9]
	v_pk_mul_f32 v[2:3], v[190:191], v[6:7]
	global_store_dwordx4 v[4:5], v[0:3], off
	v_pk_mul_f32 v[6:7], v[70:71], v[38:39] op_sel_hi:[0,1]
	v_pk_mul_f32 v[8:9], v[70:71], v[36:37] op_sel_hi:[0,1]
	v_pk_mul_f32 v[0:1], v[192:193], v[8:9]
	v_pk_mul_f32 v[2:3], v[194:195], v[6:7]
	global_store_dwordx4 v[4:5], v[0:3], off offset:1024
	v_pk_mul_f32 v[6:7], v[70:71], v[42:43] op_sel_hi:[0,1]
	v_pk_mul_f32 v[8:9], v[70:71], v[40:41] op_sel_hi:[0,1]
	v_pk_mul_f32 v[0:1], v[196:197], v[8:9]
	v_pk_mul_f32 v[2:3], v[198:199], v[6:7]
	global_store_dwordx4 v[4:5], v[0:3], off offset:2048
	v_pk_mul_f32 v[6:7], v[70:71], v[46:47] op_sel_hi:[0,1]
	v_pk_mul_f32 v[8:9], v[70:71], v[44:45] op_sel_hi:[0,1]
	v_pk_mul_f32 v[0:1], v[200:201], v[8:9]
	v_pk_mul_f32 v[2:3], v[202:203], v[6:7]
	global_store_dwordx4 v[4:5], v[0:3], off offset:3072
	v_add_co_u32_e32 v4, vcc, s25, v64
	v_pk_mul_f32 v[6:7], v[70:71], v[50:51] op_sel_hi:[0,1]
	v_pk_mul_f32 v[8:9], v[70:71], v[48:49] op_sel_hi:[0,1]
	v_addc_co_u32_e32 v5, vcc, 0, v65, vcc
	v_pk_mul_f32 v[0:1], v[204:205], v[8:9]
	v_pk_mul_f32 v[2:3], v[206:207], v[6:7]
	global_store_dwordx4 v[4:5], v[0:3], off
	v_pk_mul_f32 v[6:7], v[70:71], v[54:55] op_sel_hi:[0,1]
	v_pk_mul_f32 v[8:9], v[70:71], v[52:53] op_sel_hi:[0,1]
	v_pk_mul_f32 v[0:1], v[208:209], v[8:9]
	v_pk_mul_f32 v[2:3], v[210:211], v[6:7]
	global_store_dwordx4 v[4:5], v[0:3], off offset:1024
	v_pk_mul_f32 v[6:7], v[70:71], v[58:59] op_sel_hi:[0,1]
	v_pk_mul_f32 v[8:9], v[70:71], v[56:57] op_sel_hi:[0,1]
	v_pk_mul_f32 v[0:1], v[212:213], v[8:9]
	v_pk_mul_f32 v[2:3], v[214:215], v[6:7]
	global_store_dwordx4 v[4:5], v[0:3], off offset:2048
	v_pk_mul_f32 v[6:7], v[70:71], v[62:63] op_sel_hi:[0,1]
	v_pk_mul_f32 v[8:9], v[70:71], v[60:61] op_sel_hi:[0,1]
	v_pk_mul_f32 v[0:1], v[216:217], v[8:9]
	v_pk_mul_f32 v[2:3], v[218:219], v[6:7]
	global_store_dwordx4 v[4:5], v[0:3], off offset:3072
